# prompt scans: sixth items moved from the heaviest blocks (128..255) to the lightest (384..511), on top of v37
# baseline (speedup 1.0000x reference)
.LBB0_608:
	v_readlane_b32 s2, v254, 31
	v_readlane_b32 s3, v254, 32
	v_readlane_b32 s36, v253, 39
	s_xor_b64 s[2:3], s[2:3], -1
	v_lshl_or_b32 v2, v199, 11, v75
	v_readlane_b32 s50, v253, 53
	s_movk_i32 s24, 0xbf
	v_mov_b32_e32 v1, 0
	v_lshlrev_b32_e32 v0, 1, v198
	v_readlane_b32 s51, v253, 54
	s_add_u32 s25, s50, 0x3000000
	v_add_u32_e32 v96, v2, v197
	v_readlane_b32 s84, v253, 6
	v_readlane_b32 s82, v254, 7
	v_cmp_lt_u32_e64 s[6:7], 63, v196
	v_cmp_lt_u32_e64 s[8:9], s24, v196
	v_add_u32_e32 v103, 0x540, v196
	s_waitcnt vmcnt(9)
	v_add_u32_e32 v105, 0x3c0, v196
	v_or_b32_e32 v92, v2, v197
	v_cmp_lt_u32_e64 s[10:11], 7, v93
	s_waitcnt vmcnt(8)
	v_add_u32_e32 v107, 0x940, v79
	v_add_u32_e32 v109, 0x7c0, v79
	v_lshl_add_u64 v[94:95], s[28:29], 0, v[0:1]
	s_addc_u32 s33, s51, 0
	v_add_u32_e32 v98, v2, v73
	v_add_u32_e32 v100, v2, v71
	v_add_u32_e32 v102, v2, v69
	v_add_u32_e32 v104, 64, v96
	s_movk_i32 s54, 0x50
	v_add_u32_e32 v106, 0x50, v96
	v_add_u32_e32 v108, 0x60, v96
	v_add_u32_e32 v110, 0x70, v96
	s_mov_b32 s17, 0
	s_movk_i32 s55, 0x3880
	s_mov_b64 s[18:19], 0x1000
	s_mov_b64 s[20:21], 0x1400
	s_mov_b32 s56, 0x3fb8aa3b
	s_mov_b32 s57, 0xc2ce8ed0
	s_mov_b32 s58, 0x42b17218
	s_movk_i32 s59, 0x110
	v_mov_b32_e32 v111, 0x3ecc95a3
	s_movk_i32 s61, 0x280
	v_mov_b32_e32 v162, 0x7f800000
	v_mov_b32_e32 v112, 0x3f317218
	v_mov_b32_e32 v163, 16
	s_mov_b32 s62, s84
	s_movk_i32 s98, 0x800
	s_cmpk_lt_u32 s84, 0x180
	s_cbranch_scc1 .Lssd6_lim
	s_movk_i32 s98, 0x880

.LBB0_609:
	s_cmpk_ge_i32 s62, 0x780
	s_cselect_b32 vcc_lo, 0x80, s60
	s_add_i32 s62, s62, vcc_lo
	s_cmp_lt_i32 s62, s98
	s_cbranch_scc0 .LBB0_697
